# plus batched Q staging loads in neighbourhood-attention prologue
# baseline (speedup 1.0000x reference)
; __device__ __forceinline__ int v_st(int k, int c) { const int kk = (k & ~0xC) | ((k & 4) << 1) | ((k & 8) >> 1); return ((kk >> 3) * 4 + (c >> 5)) * 512 + ((kk & 7) * 32 + (c & 31)) * 2; }
; __device__ __forceinline__ int v_rd_base(int lane) { return ((lane & 3) << 3) | (((lane >> 2) & 3) << 6) | (((lane >> 4) & 1) << 5) | (((lane >> 5) & 1) << 8); }
; #define SLOAD(i, k0) do { sr_[i].vs0 = *reinterpret_cast<const bf16x8*>(&Vh[(long)((k0) + sr) * LDP + sc]); sr_[i].vs1 = *reinterpret_cast<const bf16x8*>(&Vh[(long)((k0) + 32 + sr) * LDP + sc]); \
;     sr_[i].ks0 = *reinterpret_cast<const bf16x8*>(&Kh[(long)((k0) + ksr) * LDP + ksc]); if (DK == 128) sr_[i].ks1 = *reinterpret_cast<const bf16x8*>(&Kh[(long)((k0) + 32 + ksr) * LDP + ksc]); } while (0)
; template <int DK, bool NA, bool QL, int SD> ...
;     ...
;   const bf16* Qw = Qb + (long)(wid * 32 + r32) * LDP + hi * 8;
; #pragma unroll
;   for (int d0 = 0; d0 < DK / 16; ++d0) { const bf16x8 qv = *reinterpret_cast<const bf16x8*>(Qw + d0 * 16); if (QL) *reinterpret_cast<bf16x8*>(ql + d0 * 1024) = qv; else qr[d0] = qv; }
;   const int sr = tid >> 4, sc = (tid & 15) * 8, vst0 = v_st(sr, sc), vst1 = v_st(32 + sr, sc);
;   const int ksr = DK == 128 ? sr : (tid >> 3), ksc = DK == 128 ? sc : (tid & 7) * 8;
;   const int vb0 = (int)(uintptr_t)V_lds + v_rd_base(lane);
;   struct { bf16x8 vs0, vs1, ks0, ks1; } sr_[SD];
;     ...
;   f32x16 pA0, pA1, pB0, pB1; float mnA, mnB, alA, alB; bf16x8 pa0, pa1, pa2, pa3;
;   constexpr int SE = 0, SO = SD - 1;
;   SLOAD(SE, 0); asm volatile("s_waitcnt vmcnt(0)" ::: "memory"); SWRITE(0, SE); __syncthreads();
.LBB0_382:
	s_or_b64 exec, exec, s[0:1]
	v_mov_b32_e32 v36, v188
	v_readlane_b32 s0, v254, 57
	v_ashrrev_i32_e32 v0, 6, v36
	v_and_b32_e32 v38, 63, v36
	v_lshl_add_u32 v2, v0, 13, s0
	v_readlane_b32 s0, v253, 0
	v_and_b32_e32 v37, 31, v36
	v_lshlrev_b32_e32 v42, 4, v38
	v_readlane_b32 s1, v253, 1
	v_bfe_u32 v34, v36, 5, 1
	v_add_u32_e32 v147, v2, v42
	v_lshl_or_b32 v0, v0, 5, v37
	v_mov_b64_e32 v[2:3], s[0:1]
	s_movk_i32 s0, 0x2800
	v_mad_i64_i32 v[2:3], s[0:1], v0, s0, v[2:3]
	v_lshlrev_b32_e32 v0, 4, v34
	v_lshl_add_u64 v[6:7], v[2:3], 0, v[0:1]
	global_load_dwordx4 v[2:5], v[6:7], off
	global_load_dwordx4 v[44:47], v[6:7], off offset:32
	global_load_dwordx4 v[48:51], v[6:7], off offset:64
	global_load_dwordx4 v[52:55], v[6:7], off offset:96
	global_load_dwordx4 v[56:59], v[6:7], off offset:128
	global_load_dwordx4 v[60:63], v[6:7], off offset:160
	global_load_dwordx4 v[64:67], v[6:7], off offset:192
	global_load_dwordx4 v[68:71], v[6:7], off offset:224
	v_ashrrev_i32_e32 v39, 4, v36
	v_add_u32_e32 v20, 32, v39
	s_movk_i32 s4, 0x1400
	v_readlane_b32 s2, v253, 4
	v_readlane_b32 s3, v253, 5
	v_lshlrev_b32_e32 v35, 8, v37
	v_or_b32_e32 v43, 32, v0
	v_lshlrev_b32_e32 v6, 1, v20
	s_waitcnt vmcnt(7)
	ds_write_b128 v147, v[2:5]
	s_waitcnt vmcnt(6)
	ds_write_b128 v147, v[44:47] offset:1024
	s_waitcnt vmcnt(5)
	ds_write_b128 v147, v[48:51] offset:2048
	s_waitcnt vmcnt(4)
	ds_write_b128 v147, v[52:55] offset:3072
	s_waitcnt vmcnt(3)
	ds_write_b128 v147, v[56:59] offset:4096
	s_waitcnt vmcnt(2)
	ds_write_b128 v147, v[60:63] offset:5120
	s_waitcnt vmcnt(1)
	ds_write_b128 v147, v[64:67] offset:6144
	s_waitcnt vmcnt(0)
	ds_write_b128 v147, v[68:71] offset:7168
	v_and_b32_e32 v3, 0xfffff0, v39
	v_lshlrev_b32_e32 v4, 1, v39
	v_lshlrev_b32_e32 v2, 3, v36
	v_and_or_b32 v3, v4, 8, v3
	v_and_b32_e32 v40, 0x78, v2
	v_lshrrev_b32_e32 v4, 1, v39
	v_lshrrev_b32_e32 v3, 1, v3
	v_bfe_u32 v2, v2, 5, 2
	v_and_b32_e32 v5, 3, v39
	v_or_b32_e32 v3, v3, v2
	v_and_or_b32 v4, v4, 4, v5
	v_lshlrev_b32_e32 v18, 1, v40
	v_lshlrev_b32_e32 v3, 9, v3
	v_lshlrev_b32_e32 v4, 6, v4
	v_and_b32_e32 v5, 48, v18
	v_or3_b32 v19, v3, v4, v5
	v_and_b32_e32 v3, 0xfffff0, v20
	v_and_or_b32 v3, v6, 8, v3
	v_lshrrev_b32_e32 v3, 1, v3
	v_or_b32_e32 v2, v3, v2
	v_lshlrev_b32_e32 v2, 9, v2
	v_or3_b32 v21, v2, v4, v5
	v_mad_i64_i32 v[2:3], s[0:1], v39, s4, 0
	v_or_b32_e32 v2, v2, v40
	v_lshlrev_b64 v[10:11], 1, v[2:3]
	v_lshl_add_u64 v[2:3], s[2:3], 0, v[10:11]
	global_load_dwordx4 v[2:5], v[2:3], off
	v_mad_i64_i32 v[6:7], s[0:1], v20, s4, 0
	v_or_b32_e32 v6, v6, v40
	v_lshlrev_b64 v[14:15], 1, v[6:7]
	v_lshl_add_u64 v[6:7], s[2:3], 0, v[14:15]
	v_readlane_b32 s0, v253, 2
	global_load_dwordx4 v[6:9], v[6:7], off
	v_readlane_b32 s1, v253, 3
	v_add_u32_e32 v152, 0, v19
	v_add_u32_e32 v153, 0, v21
	v_lshl_add_u64 v[10:11], s[0:1], 0, v[10:11]
	v_lshl_add_u64 v[14:15], s[0:1], 0, v[14:15]
	global_load_dwordx4 v[10:13], v[10:11], off
	v_readlane_b32 s0, v255, 28
	global_load_dwordx4 v[14:17], v[14:15], off
	s_waitcnt vmcnt(0)
	v_readlane_b32 s1, v255, 29
	s_waitcnt vmcnt(3)
	ds_write_b128 v152, v[2:5]
	v_lshlrev_b32_e32 v2, 8, v39
	v_and_b32_e32 v3, 0x70, v36
	v_bitop3_b32 v2, v18, v2, v3 bitop3:0xde
	v_add_u32_e32 v156, 0, v2
	v_lshlrev_b32_e32 v2, 8, v20
	v_bitop3_b32 v2, v18, v2, v3 bitop3:0xde
	v_add_u32_e32 v157, 0, v2
	v_lshlrev_b32_e32 v2, 4, v36
	v_and_b32_e32 v41, 0x70, v2
	s_waitcnt vmcnt(2)
	ds_write_b128 v153, v[6:9]
	v_bitop3_b32 v6, v0, v35, v41 bitop3:0xde
	v_add_u32_e32 v158, 0, v6
	s_waitcnt vmcnt(1)
	ds_write_b128 v156, v[10:13] offset:32768
	v_bitop3_b32 v43, v43, v35, v41 bitop3:0xde
	s_waitcnt vmcnt(0)
	ds_write_b128 v157, v[14:17] offset:32768
	s_waitcnt lgkmcnt(0)
	s_barrier
; __device__ __forceinline__ int crow(int r, int hi) { return (r & 3) + 8 * (r >> 2) + 4 * hi; }
; template <int DK, bool QL>
; __device__ __forceinline__ void qkt(f32x16& p0, f32x16& p1, const bf16* Ks, const bf16x8* qr, const char* ql, int r32, int hi) {
;   p0 = f32x16{}; p1 = f32x16{};
; #pragma unroll
;   for (int d0 = 0; d0 < DK / 16; ++d0) { int cb = (d0 * 16 + hi * 8) * 2;
;     const bf16x8 qv = QL ? *reinterpret_cast<const bf16x8*>(ql + d0 * 1024) : qr[d0];
;     bf16x8 b0 = *reinterpret_cast<const bf16x8*>((const char*)Ks + kswz<DK>(r32, cb));
;     bf16x8 b1 = *reinterpret_cast<const bf16x8*>((const char*)Ks + kswz<DK>(32 + r32, cb));
;     p0 = __builtin_amdgcn_mfma_f32_32x32x16_bf16(b0, qv, p0, 0, 0, 0);
;     p1 = __builtin_amdgcn_mfma_f32_32x32x16_bf16(b1, qv, p1, 0, 0, 0); }
; }
; __device__ __forceinline__ void na_hook(f32x16& p0, f32x16& p1, int kr, int q_row, int q_col, int win_r, int win_c, const float* rpb, float inv_scale, int hi) {
;   const bool rowok = (kr >= win_r) && (kr < win_r + 8);
;   int ir = kr - q_row + 7; ir = ir < 0 ? 0 : (ir > 14 ? 14 : ir);
;   const float* rp = rpb + ir * 31;
; #pragma unroll
;   for (int r = 0; r < 16; ++r) {
;     const int kc = crow(r, hi);
;     { const bool ok = rowok && kc >= win_c && kc < win_c + 16; int ic = kc - q_col + 15; ic = ic < 0 ? 0 : (ic > 30 ? 30 : ic);
;       p0[r] = ok ? fmaf(rp[ic], inv_scale, p0[r]) : -1e30f; }
;     { const int kc2 = kc + 32; const bool ok = rowok && kc2 >= win_c && kc2 < win_c + 16; int ic = kc2 - q_col + 15; ic = ic < 0 ? 0 : (ic > 30 ? 30 : ic);
;       p1[r] = ok ? fmaf(rp[ic], inv_scale, p1[r]) : -1e30f; }
;   }
; }
	ds_read_b128 v[2:5], v147
	ds_read_b128 v[6:9], v158 offset:32768
	ds_read_b128 v[10:13], v158 offset:40960
	s_waitcnt lgkmcnt(1)
	v_mfma_f32_32x32x16_bf16 v[18:33], v[6:9], v[2:5], 0
	v_add_u32_e32 v159, 0, v43
	ds_read_b128 v[44:47], v147 offset:1024
	ds_read_b128 v[48:51], v159 offset:32768
	ds_read_b128 v[52:55], v159 offset:40960
	v_or_b32_e32 v43, 64, v0
	v_bitop3_b32 v43, v43, v35, v41 bitop3:0xde
	v_add_u32_e32 v160, 0, v43
	v_or_b32_e32 v43, 0x60, v0
	s_waitcnt lgkmcnt(3)
	v_mfma_f32_32x32x16_bf16 v[2:17], v[10:13], v[2:5], 0
	v_bitop3_b32 v43, v43, v35, v41 bitop3:0xde
	v_add_u32_e32 v161, 0, v43
	v_or_b32_e32 v43, 0x80, v0
	v_bitop3_b32 v43, v43, v35, v41 bitop3:0xde
	v_add_u32_e32 v176, 0, v43
	v_or_b32_e32 v43, 0xa0, v0
	v_bitop3_b32 v43, v43, v35, v41 bitop3:0xde
	s_waitcnt lgkmcnt(1)
	v_mfma_f32_32x32x16_bf16 v[18:33], v[48:51], v[44:47], v[18:33]
	v_add_u32_e32 v177, 0, v43
	v_or_b32_e32 v43, 0xc0, v0
	v_bitop3_b32 v43, v43, v35, v41 bitop3:0xde
	v_add_u32_e32 v207, 0, v43
	v_or_b32_e32 v0, 0xe0, v0
	v_bitop3_b32 v0, v0, v35, v41 bitop3:0xde
	v_add_u32_e32 v208, 0, v0
	s_waitcnt lgkmcnt(0)
	v_mfma_f32_32x32x16_bf16 v[2:17], v[52:55], v[44:47], v[2:17]
	ds_read_b128 v[44:47], v147 offset:2048
	ds_read_b128 v[48:51], v160 offset:32768
	ds_read_b128 v[52:55], v160 offset:40960
	v_lshlrev_b32_e32 v0, 2, v34
	v_cmp_lt_u32_e64 s[2:3], v0, v182
	v_mov_b32_e32 v34, 0xf149f2ca
	v_sub_u32_e32 v41, v0, v181
	v_writelane_b32 v255, s2, 50
	s_waitcnt lgkmcnt(1)
	v_mfma_f32_32x32x16_bf16 v[18:33], v[48:51], v[44:47], v[18:33]
	v_mov_b32_e32 v43, 0xf149f2ca
	v_writelane_b32 v255, s3, 51
	s_nor_b64 s[2:3], s[0:1], s[2:3]
	s_waitcnt lgkmcnt(0)
	v_mfma_f32_32x32x16_bf16 v[2:17], v[52:55], v[44:47], v[2:17]
	ds_read_b128 v[44:47], v147 offset:3072
	ds_read_b128 v[48:51], v161 offset:32768
	ds_read_b128 v[52:55], v161 offset:40960
	s_waitcnt lgkmcnt(1)
	v_mfma_f32_32x32x16_bf16 v[18:33], v[48:51], v[44:47], v[18:33]
	s_waitcnt lgkmcnt(0)
	v_mfma_f32_32x32x16_bf16 v[2:17], v[52:55], v[44:47], v[2:17]
	ds_read_b128 v[44:47], v147 offset:4096
	ds_read_b128 v[48:51], v176 offset:32768
	ds_read_b128 v[52:55], v176 offset:40960
	s_waitcnt lgkmcnt(1)
	v_mfma_f32_32x32x16_bf16 v[18:33], v[48:51], v[44:47], v[18:33]
	s_waitcnt lgkmcnt(0)
	v_mfma_f32_32x32x16_bf16 v[2:17], v[52:55], v[44:47], v[2:17]
	ds_read_b128 v[44:47], v147 offset:5120
	ds_read_b128 v[48:51], v177 offset:32768
	ds_read_b128 v[52:55], v177 offset:40960
	s_waitcnt lgkmcnt(1)
	v_mfma_f32_32x32x16_bf16 v[18:33], v[48:51], v[44:47], v[18:33]
	s_waitcnt lgkmcnt(0)
	v_mfma_f32_32x32x16_bf16 v[2:17], v[52:55], v[44:47], v[2:17]
	ds_read_b128 v[44:47], v147 offset:6144
	ds_read_b128 v[48:51], v207 offset:32768
	ds_read_b128 v[52:55], v207 offset:40960
	s_waitcnt lgkmcnt(1)
	v_mfma_f32_32x32x16_bf16 v[18:33], v[48:51], v[44:47], v[18:33]
	s_waitcnt lgkmcnt(0)
	v_mfma_f32_32x32x16_bf16 v[2:17], v[52:55], v[44:47], v[2:17]
	ds_read_b128 v[44:47], v147 offset:7168
	ds_read_b128 v[48:51], v208 offset:32768
	ds_read_b128 v[52:55], v208 offset:40960
	s_waitcnt lgkmcnt(1)
	v_mfma_f32_32x32x16_bf16 v[18:33], v[48:51], v[44:47], v[18:33]
	s_waitcnt lgkmcnt(0)
	v_mfma_f32_32x32x16_bf16 v[2:17], v[52:55], v[44:47], v[2:17]
	s_and_saveexec_b64 s[0:1], s[2:3]
	s_cbranch_execz .LBB0_384
	v_sub_u32_e32 v35, v0, v181
	v_max_i32_e32 v35, -15, v35
	v_lshl_add_u32 v35, v35, 2, v183
	ds_read_b32 v35, v35 offset:928
	s_waitcnt lgkmcnt(0)
	s_nop 2
	v_fmamk_f32 v43, v35, 0x413504f3, v18
